# attention L0: L2 prefetch of the item's gate rows and next item's Q rows by dummy LDS-DMA dword loads after every key-block DMA issue
# baseline (speedup 1.0000x reference)
; __device__ __forceinline__ void attn_phase(const Params& p, LAS unsigned char* lds, int li, int tid, int G, bf16_t* __restrict__ dst, const bf16_t* __restrict__ ZGA) {
;     ...
;     auto load_q = [&](int item, int lq_, int g_) {
;         const int tb = item >> 2, hk = item & 3;
; #pragma unroll
;         for (int mb = 0; mb < 3; ++mb) {
;             const int hh = mb, r = 16 * w + lq_;
;             const bf16_t* qp = Z0 + (size_t)(tb * 128 + r) * 2048 + (3 * hk + hh) * 128 + 8 * g_;
; #pragma unroll
;             for (int ks = 0; ks < 4; ++ks) qraw[mb][ks] = *(const u32x4*)(qp + 32 * ks);
;         }
;     };
;     ...
;         u32x2 gv[3][8];
; #pragma unroll
;         for (int mb = 0; mb < 3; ++mb) {
;             const int hh = mb, r = 16 * w + lq;
;             const bf16_t* gp = ZGA + (size_t)(t0 + r) * 1536 + (3 * hk + hh) * 128 + 4 * g;
; #pragma unroll
;             for (int db = 0; db < 8; ++db) gv[mb][db] = *(const u32x2*)(gp + 16 * db);
;         }
.LBB0_331:
	v_mbcnt_lo_u32_b32 v146, -1, 0
	v_mbcnt_hi_u32_b32 v146, -1, v146
	s_lshl_b32 s4, s38, 7
	s_add_i32 s4, s4, s35
	s_mul_i32 s4, s4, 0xc00
	s_mul_i32 s5, s46, 0x300
	s_add_u32 s4, s4, s5
	s_add_u32 s4, s26, s4
	s_addc_u32 s5, s27, 0
	s_cmp_lt_i32 s97, 0
	s_cselect_b32 s62, s34, s97
	s_and_b32 s63, s62, 3
	s_lshl_b32 s62, s62, 5
	s_and_b32 s62, s62, 0xffffff80
	s_add_i32 s62, s62, s35
	s_lshl_b32 s62, s62, 12
	s_mul_i32 s63, s63, 0x300
	s_add_u32 s62, s62, s63
	s_add_u32 s62, s20, s62
	s_addc_u32 s63, s21, 0
	s_mov_b32 m0, 0x25400
	s_movk_i32 s18, 0xc00
	v_mul_u32_u24_e32 v147, 43, v146
	v_lshrrev_b32_e32 v147, 8, v147
	v_mul_u32_u24_e32 v148, 6, v147
	v_sub_u32_e32 v148, v146, v148
	v_lshlrev_b32_e32 v148, 7, v148
	v_mad_u32_u24 v149, v147, s18, v148
	v_lshl_add_u32 v150, v147, 12, v148
	global_load_lds_dword v149, s[4:5]
	global_load_lds_dword v150, s[62:63]
	v_add_u32_e32 v146, 64, v146
	v_mul_u32_u24_e32 v147, 43, v146
	v_lshrrev_b32_e32 v147, 8, v147
	v_mul_u32_u24_e32 v148, 6, v147
	v_sub_u32_e32 v148, v146, v148
	v_lshlrev_b32_e32 v148, 7, v148
	v_mad_u32_u24 v149, v147, s18, v148
	v_lshl_add_u32 v150, v147, 12, v148
	global_load_lds_dword v149, s[4:5]
	global_load_lds_dword v150, s[62:63]
	s_cmp_eq_u32 s0, 1
	s_cselect_b64 s[4:5], -1, 0
	s_and_b64 s[4:5], s[48:49], s[4:5]
	s_and_b64 s[62:63], s[4:5], exec
	s_cselect_b32 s18, 0, 2
	s_and_b64 s[62:63], s[58:59], exec
	s_cselect_b32 s18, 1, s18
	s_xor_b64 s[62:63], s[58:59], -1
	s_and_b64 s[4:5], s[62:63], s[4:5]
	v_lshl_add_u32 v188, s18, 7, v183
	s_mov_b32 s0, 0
	s_xor_b64 s[62:63], s[4:5], -1
	v_add3_u32 v0, s64, v174, v175
	v_lshlrev_b32_e32 v189, 2, v188
	v_add_u32_e32 v190, s19, v184
	v_add_u32_e32 v191, s19, v185
	v_add_u32_e32 v192, s19, v186
	v_add_u32_e32 v193, s19, v187
	v_mov_b32_e32 v194, v176
	s_branch .LBB0_334
